# NSA fast path: QK MFMAs of row set 1 woven into the exp block of row set 0
# baseline (speedup 1.0000x reference)
; __device__ __forceinline__ f32x4 mfma16(bf16x8 a, bf16x8 b, f32x4 c) { return __builtin_amdgcn_mfma_f32_16x16x32_bf16(a, b, c, 0, 0, 0); }
; template <int MODE> __device__ __forceinline__ void tile_softmax(f32x4 (&S)[4], bool rowv, int kfirst, int klo, unsigned kspan, float& l) {
;     ...
;         for (int j = 0; j < 4; ++j) { float e = __builtin_amdgcn_exp2f(S[st][j]);
;             if (MODE == 1) e = rowv ? e : 0.f;
;             if (MODE == 2) e = ((unsigned)(kfirst + st * 16 + j - klo) <= kspan) ? e : 0.f;
;             S[st][j] = e; ps += e; }
;     l += ps;
; __device__ __forceinline__ void nsa_scores(const bf16x8 (&ka)[4], const bf16x8 (&kb)[4], bf16x8 q0, bf16x8 q1, f32x4 (&S)[4]) {
;     const f32x4 zero4 = {0.f, 0.f, 0.f, 0.f};
; #pragma unroll
;     for (int st = 0; st < 4; ++st) S[st] = mfma16(ka[st], q0, zero4);
; #pragma unroll
;     for (int st = 0; st < 4; ++st) S[st] = mfma16(kb[st], q1, S[st]);
; }
.Lsel_fast_k:
	v_add_u32_e32 v126, s45, v197
	v_add_u32_e32 v127, s45, v198
	v_add_u32_e32 v128, s45, v199
	v_add_u32_e32 v129, s45, v206
	s_waitcnt lgkmcnt(0)
	s_and_b64 vcc, exec, s[56:57]
	s_cbranch_vccz .Lsf_only1
	s_and_b64 vcc, exec, s[28:29]
	s_cbranch_vccz .Lsf_only0
	v_mfma_f32_16x16x32_bf16 v[16:19], v[132:135], v[60:63], 0
	v_mfma_f32_16x16x32_bf16 v[20:23], v[136:139], v[60:63], 0
	v_mfma_f32_16x16x32_bf16 v[24:27], v[140:143], v[60:63], 0
	v_mfma_f32_16x16x32_bf16 v[28:31], v[144:147], v[60:63], 0
	v_mfma_f32_16x16x32_bf16 v[16:19], v[148:151], v[72:75], v[16:19]
	v_mfma_f32_16x16x32_bf16 v[20:23], v[152:155], v[72:75], v[20:23]
	v_mfma_f32_16x16x32_bf16 v[24:27], v[116:119], v[72:75], v[24:27]
	v_mfma_f32_16x16x32_bf16 v[28:31], v[120:123], v[72:75], v[28:31]
	v_mfma_f32_16x16x32_bf16 v[32:35], v[132:135], v[76:79], 0
	v_mfma_f32_16x16x32_bf16 v[36:39], v[136:139], v[76:79], 0
	v_mfma_f32_16x16x32_bf16 v[40:43], v[140:143], v[76:79], 0
	v_mfma_f32_16x16x32_bf16 v[44:47], v[144:147], v[76:79], 0
	s_nop 0
	v_exp_f32_e32 v16, v16
	v_exp_f32_e32 v17, v17
	v_exp_f32_e32 v18, v18
	v_exp_f32_e32 v19, v19
	v_mfma_f32_16x16x32_bf16 v[32:35], v[148:151], v[80:83], v[32:35]
	v_exp_f32_e32 v20, v20
	v_exp_f32_e32 v21, v21
	v_exp_f32_e32 v22, v22
	v_exp_f32_e32 v23, v23
	v_mfma_f32_16x16x32_bf16 v[36:39], v[152:155], v[80:83], v[36:39]
	v_exp_f32_e32 v24, v24
	v_exp_f32_e32 v25, v25
	v_exp_f32_e32 v26, v26
	v_exp_f32_e32 v27, v27
	v_mfma_f32_16x16x32_bf16 v[40:43], v[116:119], v[80:83], v[40:43]
	v_exp_f32_e32 v28, v28
	v_exp_f32_e32 v29, v29
	v_exp_f32_e32 v30, v30
	v_exp_f32_e32 v31, v31
	v_mfma_f32_16x16x32_bf16 v[44:47], v[120:123], v[80:83], v[44:47]
	s_nop 3
	ds_read_b64 v[132:133], v126 offset:8192
	ds_read_b64 v[134:135], v127 offset:8192
	ds_read_b64 v[148:149], v128 offset:8192
	ds_read_b64 v[150:151], v129 offset:8192
	ds_read_b64 v[136:137], v126 offset:10240
	ds_read_b64 v[138:139], v127 offset:10240
	ds_read_b64 v[152:153], v128 offset:10240
	ds_read_b64 v[154:155], v129 offset:10240
	ds_read_b64 v[140:141], v126 offset:12288
	ds_read_b64 v[142:143], v127 offset:12288
	ds_read_b64 v[116:117], v128 offset:12288
	ds_read_b64 v[118:119], v129 offset:12288
	ds_read_b64 v[144:145], v126 offset:14336
	ds_read_b64 v[146:147], v127 offset:14336
	ds_read_b64 v[120:121], v128 offset:14336
	ds_read_b64 v[122:123], v129 offset:14336
	v_add_f32_e32 v124, 0, v16
	v_add_f32_e32 v124, v124, v17
	v_add_f32_e32 v124, v124, v18
	v_add_f32_e32 v124, v124, v19
	v_add_f32_e32 v124, v124, v20
	v_add_f32_e32 v124, v124, v21
	v_add_f32_e32 v124, v124, v22
	v_add_f32_e32 v124, v124, v23
	v_add_f32_e32 v124, v124, v24
	v_add_f32_e32 v124, v124, v25
	v_add_f32_e32 v124, v124, v26
	v_add_f32_e32 v124, v124, v27
	v_add_f32_e32 v124, v124, v28
	v_add_f32_e32 v124, v124, v29
	v_add_f32_e32 v124, v124, v30
	v_add_f32_e32 v124, v124, v31
	s_cmp_eq_u64 s[98:99], -1
	s_cbranch_scc1 .Lsf_b0_a
	v_cndmask_b32_e64 v125, 0, -1, s[98:99]
	v_and_b32_e32 v124, v124, v125
